# combo6 + GEMM main loop head aligned to 64 bytes
# speedup vs baseline: 1.0017x; 1.0017x over previous
.LBB0_92:
	s_add_u32 s12, s12, 0x100
	s_addc_u32 s13, s13, 0
	s_add_u32 s8, s14, 0x80
	v_mov_b32_e32 v0, 0
	s_addc_u32 s9, s15, 0
	s_mov_b32 s10, 0
	v_mov_b32_e32 v1, v0
	v_mov_b32_e32 v2, v0
	v_mov_b32_e32 v3, v0
	v_mov_b32_e32 v4, v0
	v_mov_b32_e32 v5, v0
	v_mov_b32_e32 v6, v0
	v_mov_b32_e32 v7, v0
	v_mov_b32_e32 v16, v0
	v_mov_b32_e32 v17, v0
	v_mov_b32_e32 v18, v0
	v_mov_b32_e32 v19, v0
	v_mov_b32_e32 v20, v0
	v_mov_b32_e32 v21, v0
	v_mov_b32_e32 v22, v0
	v_mov_b32_e32 v23, v0
	v_mov_b32_e32 v32, v0
	v_mov_b32_e32 v33, v0
	v_mov_b32_e32 v34, v0
	v_mov_b32_e32 v35, v0
	v_mov_b32_e32 v36, v0
	v_mov_b32_e32 v37, v0
	v_mov_b32_e32 v38, v0
	v_mov_b32_e32 v39, v0
	s_waitcnt vmcnt(0)
	v_mov_b32_e32 v48, v0
	v_mov_b32_e32 v49, v0
	v_mov_b32_e32 v50, v0
	v_mov_b32_e32 v51, v0
	v_mov_b32_e32 v52, v0
	v_mov_b32_e32 v53, v0
	v_mov_b32_e32 v54, v0
	v_mov_b32_e32 v55, v0
	v_mov_b32_e32 v8, v0
	v_mov_b32_e32 v9, v0
	v_mov_b32_e32 v10, v0
	v_mov_b32_e32 v11, v0
	v_mov_b32_e32 v12, v0
	v_mov_b32_e32 v13, v0
	v_mov_b32_e32 v14, v0
	v_mov_b32_e32 v15, v0
	v_mov_b32_e32 v24, v0
	v_mov_b32_e32 v25, v0
	v_mov_b32_e32 v26, v0
	v_mov_b32_e32 v27, v0
	v_mov_b32_e32 v28, v0
	v_mov_b32_e32 v29, v0
	v_mov_b32_e32 v30, v0
	v_mov_b32_e32 v31, v0
	v_mov_b32_e32 v40, v0
	v_mov_b32_e32 v41, v0
	v_mov_b32_e32 v42, v0
	v_mov_b32_e32 v43, v0
	v_mov_b32_e32 v44, v0
	v_mov_b32_e32 v45, v0
	v_mov_b32_e32 v46, v0
	v_mov_b32_e32 v47, v0
	v_mov_b32_e32 v56, v0
	v_mov_b32_e32 v57, v0
	v_mov_b32_e32 v58, v0
	v_mov_b32_e32 v59, v0
	v_mov_b32_e32 v60, v0
	v_mov_b32_e32 v61, v0
	v_mov_b32_e32 v62, v0
	v_mov_b32_e32 v63, v0
	s_waitcnt lgkmcnt(0)
	v_mov_b32_e32 v64, v0
	v_mov_b32_e32 v65, v0
	v_mov_b32_e32 v66, v0
	v_mov_b32_e32 v67, v0
	v_mov_b32_e32 v68, v0
	v_mov_b32_e32 v69, v0
	v_mov_b32_e32 v70, v0
	v_mov_b32_e32 v71, v0
	v_mov_b32_e32 v80, v0
	v_mov_b32_e32 v81, v0
	v_mov_b32_e32 v82, v0
	v_mov_b32_e32 v83, v0
	v_mov_b32_e32 v84, v0
	v_mov_b32_e32 v85, v0
	v_mov_b32_e32 v86, v0
	v_mov_b32_e32 v87, v0
	v_mov_b32_e32 v96, v0
	v_mov_b32_e32 v97, v0
	v_mov_b32_e32 v98, v0
	v_mov_b32_e32 v99, v0
	v_mov_b32_e32 v100, v0
	v_mov_b32_e32 v101, v0
	v_mov_b32_e32 v102, v0
	v_mov_b32_e32 v103, v0
	v_mov_b32_e32 v112, v0
	v_mov_b32_e32 v113, v0
	v_mov_b32_e32 v114, v0
	v_mov_b32_e32 v115, v0
	v_mov_b32_e32 v116, v0
	v_mov_b32_e32 v117, v0
	v_mov_b32_e32 v118, v0
	v_mov_b32_e32 v119, v0
	v_mov_b32_e32 v72, v0
	v_mov_b32_e32 v73, v0
	v_mov_b32_e32 v74, v0
	v_mov_b32_e32 v75, v0
	v_mov_b32_e32 v76, v0
	v_mov_b32_e32 v77, v0
	v_mov_b32_e32 v78, v0
	v_mov_b32_e32 v79, v0
	v_mov_b32_e32 v88, v0
	v_mov_b32_e32 v89, v0
	v_mov_b32_e32 v90, v0
	v_mov_b32_e32 v91, v0
	v_mov_b32_e32 v92, v0
	v_mov_b32_e32 v93, v0
	v_mov_b32_e32 v94, v0
	v_mov_b32_e32 v95, v0
	v_mov_b32_e32 v104, v0
	v_mov_b32_e32 v105, v0
	v_mov_b32_e32 v106, v0
	v_mov_b32_e32 v107, v0
	v_mov_b32_e32 v108, v0
	v_mov_b32_e32 v109, v0
	v_mov_b32_e32 v110, v0
	v_mov_b32_e32 v111, v0
	v_mov_b32_e32 v120, v0
	v_mov_b32_e32 v121, v0
	v_mov_b32_e32 v122, v0
	v_mov_b32_e32 v123, v0
	v_mov_b32_e32 v124, v0
	v_mov_b32_e32 v125, v0
	v_mov_b32_e32 v126, v0
	v_mov_b32_e32 v127, v0
	.p2align 6
